# final-local-barrier-flag-also-requires-grid-multiple-of-8
# baseline (speedup 1.0000x reference)
.LBB0_594:
	v_readlane_b32 s4, v253, 35
	v_readlane_b32 s5, v253, 36
	v_cmp_ne_u32_e32 vcc, 0, v15
	v_readlane_b32 s2, v251, 33
	v_cndmask_b32_e64 v16, 0, v15, s[4:5]
	v_readlane_b32 s4, v253, 33
	v_readlane_b32 s5, v253, 34
	v_cndmask_b32_e64 v15, 0, 1, vcc
	v_cmp_ne_u32_e32 vcc, 0, v0
	v_cndmask_b32_e64 v16, v16, v0, s[4:5]
	v_readlane_b32 s4, v253, 31
	v_readlane_b32 s5, v253, 32
	v_addc_co_u32_e32 v0, vcc, 0, v15, vcc
	s_nop 0
	v_cndmask_b32_e64 v16, v16, v1, s[4:5]
	v_readlane_b32 s4, v253, 29
	v_readlane_b32 s5, v253, 30
	v_cmp_ne_u32_e32 vcc, 0, v1
	s_nop 0
	v_cndmask_b32_e64 v16, v16, v2, s[4:5]
	v_readlane_b32 s4, v253, 27
	v_readlane_b32 s5, v253, 28
	v_cndmask_b32_e64 v1, 0, 1, vcc
	v_cmp_ne_u32_e32 vcc, 0, v2
	v_cndmask_b32_e64 v16, v16, v3, s[4:5]
	v_readlane_b32 s4, v253, 25
	v_readlane_b32 s5, v253, 26
	v_addc_co_u32_e32 v0, vcc, v0, v1, vcc
	s_nop 0
	v_cndmask_b32_e64 v16, v16, v4, s[4:5]
	v_readlane_b32 s4, v253, 23
	v_readlane_b32 s5, v253, 24
	v_cmp_ne_u32_e32 vcc, 0, v3
	s_nop 0
	v_cndmask_b32_e64 v16, v16, v5, s[4:5]
	v_readlane_b32 s4, v253, 21
	v_readlane_b32 s5, v253, 22
	v_cndmask_b32_e64 v1, 0, 1, vcc
	v_cmp_ne_u32_e32 vcc, 0, v4
	v_cndmask_b32_e64 v16, v16, v6, s[4:5]
	v_readlane_b32 s4, v253, 19
	v_readlane_b32 s5, v253, 20
	v_addc_co_u32_e32 v0, vcc, v0, v1, vcc
	s_nop 0
	v_cndmask_b32_e64 v16, v16, v7, s[4:5]
	v_readlane_b32 s4, v253, 17
	v_readlane_b32 s5, v253, 18
	v_cmp_ne_u32_e32 vcc, 0, v5
	s_nop 0
	v_cndmask_b32_e64 v16, v16, v8, s[4:5]
	v_readlane_b32 s4, v253, 15
	v_cndmask_b32_e64 v1, 0, 1, vcc
	v_cmp_ne_u32_e32 vcc, 0, v6
	v_readlane_b32 s5, v253, 16
	s_nop 0
	v_addc_co_u32_e32 v0, vcc, v0, v1, vcc
	v_cndmask_b32_e64 v16, v16, v9, s[4:5]
	v_readlane_b32 s4, v253, 13
	v_cmp_ne_u32_e32 vcc, 0, v7
	v_readlane_b32 s5, v253, 14
	s_nop 0
	v_cndmask_b32_e64 v1, 0, 1, vcc
	v_cmp_ne_u32_e32 vcc, 0, v8
	v_cndmask_b32_e64 v16, v16, v10, s[4:5]
	v_readlane_b32 s4, v253, 11
	v_addc_co_u32_e32 v0, vcc, v0, v1, vcc
	v_readlane_b32 s5, v253, 12
	v_cmp_ne_u32_e32 vcc, 0, v9
	s_nop 0
	v_cndmask_b32_e64 v16, v16, v11, s[4:5]
	v_readlane_b32 s4, v253, 9
	v_cndmask_b32_e64 v1, 0, 1, vcc
	v_cmp_ne_u32_e32 vcc, 0, v10
	v_readlane_b32 s5, v253, 10
	s_nop 0
	v_addc_co_u32_e32 v0, vcc, v0, v1, vcc
	v_cndmask_b32_e64 v16, v16, v12, s[4:5]
	v_readlane_b32 s4, v253, 7
	v_cmp_ne_u32_e32 vcc, 0, v11
	v_readlane_b32 s5, v253, 8
	s_nop 0
	v_cndmask_b32_e64 v1, 0, 1, vcc
	v_cmp_ne_u32_e32 vcc, 0, v12
	v_cndmask_b32_e64 v16, v16, v13, s[4:5]
	v_readlane_b32 s4, v253, 5
	v_addc_co_u32_e32 v0, vcc, v0, v1, vcc
	v_readlane_b32 s5, v253, 6
	v_cmp_ne_u32_e32 vcc, 0, v13
	s_nop 0
	v_cndmask_b32_e64 v16, v16, v14, s[4:5]
	v_cndmask_b32_e64 v1, 0, 1, vcc
	v_cmp_ne_u32_e32 vcc, 0, v14
	v_max_u32_e32 v2, 1, v16
	s_nop 0
	v_addc_co_u32_e32 v0, vcc, v0, v1, vcc
	v_mov_b32_e32 v1, s2
	v_readlane_b32 s2, v251, 34
	v_max_u32_e32 v0, 1, v0
	ds_write_b32 v1, v2
	v_mov_b32_e32 v1, s2
	ds_write_b32 v1, v0
	v_readlane_b32 s4, v253, 3
	v_readlane_b32 s5, v253, 4
	s_nop 4
	global_load_dword v4, v97, s[4:5] offset:-512 sc1
	global_load_dword v5, v97, s[4:5] offset:-448 sc1
	global_load_dword v6, v97, s[4:5] offset:-384 sc1
	global_load_dword v7, v97, s[4:5] offset:-320 sc1
	global_load_dword v8, v97, s[4:5] offset:-256 sc1
	global_load_dword v9, v97, s[4:5] offset:-192 sc1
	global_load_dword v10, v97, s[4:5] offset:-128 sc1
	global_load_dword v11, v97, s[4:5] offset:-64 sc1
	s_waitcnt vmcnt(0)
	v_add_u32_e32 v12, -1, v4
	v_and_b32_e32 v12, v4, v12
	v_mov_b32_e32 v13, v4
	v_add_u32_e32 v14, -1, v5
	v_and_b32_e32 v14, v5, v14
	v_or_b32_e32 v12, v12, v14
	v_min_u32_e32 v13, v13, v5
	v_add_u32_e32 v14, -1, v6
	v_and_b32_e32 v14, v6, v14
	v_or_b32_e32 v12, v12, v14
	v_min_u32_e32 v13, v13, v6
	v_add_u32_e32 v14, -1, v7
	v_and_b32_e32 v14, v7, v14
	v_or_b32_e32 v12, v12, v14
	v_min_u32_e32 v13, v13, v7
	v_add_u32_e32 v14, -1, v8
	v_and_b32_e32 v14, v8, v14
	v_or_b32_e32 v12, v12, v14
	v_min_u32_e32 v13, v13, v8
	v_add_u32_e32 v14, -1, v9
	v_and_b32_e32 v14, v9, v14
	v_or_b32_e32 v12, v12, v14
	v_min_u32_e32 v13, v13, v9
	v_add_u32_e32 v14, -1, v10
	v_and_b32_e32 v14, v10, v14
	v_or_b32_e32 v12, v12, v14
	v_min_u32_e32 v13, v13, v10
	v_add_u32_e32 v14, -1, v11
	v_and_b32_e32 v14, v11, v14
	v_or_b32_e32 v12, v12, v14
	v_min_u32_e32 v13, v13, v11
	v_cmp_eq_u32_e32 vcc, 0, v13
	s_nop 1
	v_cndmask_b32_e64 v14, 0, 1, vcc
	v_or_b32_e32 v12, v12, v14
	v_cmp_eq_u32_e32 vcc, 0, v12
	s_nop 1
	v_cndmask_b32_e64 v12, 0, 1, vcc
	s_nop 1
	v_readfirstlane_b32 s100, v12
	s_nop 3
	s_and_b32 s4, s15, 7
	s_cmp_eq_u32 s4, 0
	s_cselect_b32 s4, 1, 0
	s_and_b32 s100, s100, s4
